# P5 rows remapped class-aligned (class c handles batch c), P5-P6 seam becomes a class barrier; P8 start guarded by a device-wide P5-done counter
# speedup vs baseline: 1.0215x; 1.0020x over previous
.LBB0_630:
	s_and_b32 s2, s74, 7
	s_lshr_b32 s3, s74, 3
	s_lshl_b32 s1, s2, 7
	s_add_u32 s1, s1, s3
	s_mov_b32 s0, 32
	s_movk_i32 s6, 0x4000
	v_lshl_add_u32 v0, s1, 9, v10
	s_add_u32 s2, s2, 1
	s_lshl_b32 s53, s2, 16
	s_sub_u32 s53, s53, 1
	s_ashr_i32 s13, s12, 31
	v_readlane_b32 s16, v254, 10
	s_lshl_b64 s[2:3], s[12:13], 24
	v_readlane_b32 s18, v254, 12
	v_readlane_b32 s17, v254, 11
	v_readlane_b32 s19, v254, 13
	s_add_u32 s16, s18, s2
	v_ashrrev_i32_e32 v1, 31, v0
	s_addc_u32 s17, s19, s3
	v_lshl_add_u64 v[2:3], v[0:1], 4, s[8:9]
	s_mov_b64 s[2:3], 0x9e00000
	s_ashr_i32 s7, s6, 31
	v_lshlrev_b32_e32 v1, 1, v10
	v_lshl_add_u64 v[2:3], v[2:3], 0, s[2:3]
	s_lshl_b64 s[18:19], s[6:7], 4
	v_lshl_add_u32 v4, s1, 10, v1
	s_lshl_b32 s2, s0, 10
	s_mov_b64 s[38:39], 0
	v_mov_b32_e32 v1, v0
	v_readlane_b32 s20, v254, 14
	v_readlane_b32 s21, v254, 15
	v_readlane_b32 s22, v254, 16
	v_readlane_b32 s23, v254, 17
	v_readlane_b32 s24, v254, 18
	v_readlane_b32 s25, v254, 19
	v_readlane_b32 s26, v254, 20
	v_readlane_b32 s27, v254, 21
	v_readlane_b32 s28, v254, 22
	v_readlane_b32 s29, v254, 23
	v_readlane_b32 s30, v254, 24
	v_readlane_b32 s31, v254, 25

.LBB0_634:
	s_or_b64 exec, exec, s[14:15]
	s_mov_b32 s53, 0x7ffff
	s_waitcnt vmcnt(0)
	s_barrier
	s_mov_b64 s[6:7], exec
	v_readlane_b32 s0, v254, 8
	v_readlane_b32 s1, v254, 9
	s_and_b64 s[0:1], s[6:7], s[0:1]
	s_mov_b64 exec, s[0:1]
	s_cbranch_execz .LBB0_686
	v_readlane_b32 s0, v255, 41
	s_cmp_eq_u32 s0, 1
	s_cbranch_scc1 .Llb686_go
	s_cmp_eq_u32 s0, 2
	s_cbranch_scc1 .Llb686_global
	s_add_u32 s2, s92, 0x5000
	s_addc_u32 s3, s93, 0
	s_waitcnt vmcnt(0) lgkmcnt(0)
	global_load_dword v0, v197, s[2:3] offset:128 sc1
	s_waitcnt vmcnt(0)
	v_readfirstlane_b32 s0, v0
	s_cmp_eq_u32 s0, 0
	s_cselect_b32 s0, 1, 2
	s_nop 0
	v_writelane_b32 v255, s0, 41
	s_cmp_eq_u32 s0, 1
	s_cbranch_scc0 .Llb686_global
.Llb686_go:
	s_and_b32 s0, s74, 7
	s_lshl_b32 s0, s0, 8
	s_add_u32 s0, s0, 0x4000
	s_add_u32 s2, s92, s0
	s_addc_u32 s3, s93, 0
	v_mov_b32_e32 v0, 1
	s_waitcnt vmcnt(0) lgkmcnt(0)
	s_add_u32 s12, s92, 0x5100
	s_addc_u32 s13, s93, 0
	global_atomic_add v197, v0, s[12:13]
	global_atomic_add v1, v197, v0, s[2:3] sc0
	buffer_inv sc1
	s_waitcnt vmcnt(0)
	v_readfirstlane_b32 s1, v1
	s_lshr_b32 s8, s1, 5
	s_and_b32 s1, s1, 31
	s_cmp_eq_u32 s1, 31
	s_cbranch_scc1 .Llb686_lead
	s_mov_b32 s9, 0

.Llb686_fin:
	s_branch .LBB0_686

.Llb790_go:
	s_and_b32 s0, s74, 7
	s_lshl_b32 s0, s0, 8
	s_add_u32 s0, s0, 0x4000
	s_add_u32 s2, s92, s0
	s_addc_u32 s3, s93, 0
	v_mov_b32_e32 v0, 1
	s_waitcnt vmcnt(0) lgkmcnt(0)
	s_add_u32 s12, s92, 0x5100
	s_addc_u32 s13, s93, 0
	global_load_dword v2, v197, s[12:13] sc1
	global_atomic_add v1, v197, v0, s[2:3] sc0
	buffer_inv sc1
	s_waitcnt vmcnt(0)
	v_readfirstlane_b32 s1, v1
	s_lshr_b32 s8, s1, 5
	s_and_b32 s1, s1, 31
	s_cmp_eq_u32 s1, 31
	s_cbranch_scc1 .Llb790_lead
	s_mov_b32 s9, 0

.Llb790_fin:
	v_readfirstlane_b32 s1, v2
	v_readlane_b32 s0, v255, 31
	s_add_u32 s0, s0, 1
	s_lshl_b32 s0, s0, 8
	s_mov_b32 s9, 0
.Llb790_g:
	s_cmp_ge_u32 s1, s0
	s_cbranch_scc1 .LBB0_790
	s_sleep 1
	global_load_dword v2, v197, s[12:13] sc1
	s_waitcnt vmcnt(0)
	v_readfirstlane_b32 s1, v2
	s_add_u32 s9, s9, 1
	s_cmp_lt_u32 s9, 0x40000
	s_cbranch_scc1 .Llb790_g
	s_branch .LBB0_790
